# flat release poll with a longer s_sleep between grid-barrier polls (3 instead of 1)
# baseline (speedup 1.0000x reference)
.LBB0_14:
	s_sleep 3
	global_load_dword v2, v0, s[4:5] offset:32 sc1
	s_waitcnt vmcnt(0)
	v_and_b32_e32 v2, 0xffff0000, v2
	v_cmp_ne_u32_e32 vcc, v2, v1
	s_or_b64 s[6:7], vcc, s[6:7]
	s_andn2_b64 exec, exec, s[6:7]
	s_cbranch_execnz .LBB0_14

.LBB0_47:
	global_load_dword v15, v16, s[8:9] sc1
	global_load_dword v0, v16, s[10:11] sc1
	global_load_dword v1, v16, s[12:13] sc1
	global_load_dword v2, v16, s[14:15] sc1
	global_load_dword v3, v16, s[16:17] sc1
	global_load_dword v4, v16, s[18:19] sc1
	global_load_dword v5, v16, s[20:21] sc1
	global_load_dword v6, v16, s[22:23] sc1
	global_load_dword v7, v16, s[24:25] sc1
	global_load_dword v8, v16, s[26:27] sc1
	global_load_dword v9, v16, s[28:29] sc1
	global_load_dword v10, v16, s[30:31] sc1
	global_load_dword v11, v16, s[34:35] sc1
	global_load_dword v12, v16, s[36:37] sc1
	global_load_dword v13, v16, s[38:39] sc1
	global_load_dword v14, v16, s[40:41] sc1
	s_mov_b64 s[42:43], -1
	s_mov_b64 s[44:45], -1
	s_waitcnt vmcnt(14)
	v_add_u32_e32 v17, v0, v15
	s_waitcnt vmcnt(13)
	v_add_u32_e32 v17, v17, v1
	s_waitcnt vmcnt(12)
	v_add_u32_e32 v17, v17, v2
	s_waitcnt vmcnt(11)
	v_add_u32_e32 v17, v17, v3
	s_waitcnt vmcnt(10)
	v_add_u32_e32 v17, v17, v4
	s_waitcnt vmcnt(9)
	v_add_u32_e32 v17, v17, v5
	s_waitcnt vmcnt(8)
	v_add_u32_e32 v17, v17, v6
	s_waitcnt vmcnt(7)
	v_add_u32_e32 v17, v17, v7
	s_waitcnt vmcnt(6)
	v_add_u32_e32 v17, v17, v8
	s_waitcnt vmcnt(5)
	v_add_u32_e32 v17, v17, v9
	s_waitcnt vmcnt(4)
	v_add_u32_e32 v17, v17, v10
	s_waitcnt vmcnt(3)
	v_add_u32_e32 v17, v17, v11
	s_waitcnt vmcnt(2)
	v_add_u32_e32 v17, v17, v12
	s_waitcnt vmcnt(1)
	v_add_u32_e32 v17, v17, v13
	s_waitcnt vmcnt(0)
	v_add_u32_e32 v17, v17, v14
	v_cmp_eq_u32_e32 vcc, s33, v17
	s_cbranch_vccnz .LBB0_46
	s_and_b32 s42, s49, 0xff
	s_cmp_eq_u32 s42, 0
	s_mov_b64 s[42:43], -1
	s_mov_b64 s[46:47], -1
	s_sleep 3
	s_cbranch_scc0 .LBB0_51
	global_load_dword v17, v16, s[6:7] sc1
	s_waitcnt vmcnt(0)
	v_cmp_eq_u32_e32 vcc, 0, v17
	s_cbranch_vccnz .LBB0_53
	s_mov_b64 s[46:47], 0

.LBB0_65:
	s_and_b32 s22, s26, 0xff
	s_mov_b64 s[20:21], -1
	s_cmp_lg_u32 s22, 0
	s_mov_b64 s[24:25], -1
	s_sleep 3
	s_cbranch_scc1 .LBB0_68
	global_load_dword v2, v0, s[12:13] sc1
	s_waitcnt vmcnt(0)
	v_cmp_eq_u32_e32 vcc, 0, v2
	s_cbranch_vccnz .LBB0_70
	s_mov_b64 s[24:25], 0
	s_mov_b64 s[22:23], -1

.LBB0_82:
	s_and_b32 s20, s26, 0xff
	s_cmp_lg_u32 s20, 0
	s_mov_b64 s[22:23], -1
	s_sleep 3
	s_cbranch_scc1 .LBB0_85
	global_load_dword v1, v0, s[12:13] sc1
	s_waitcnt vmcnt(0)
	v_cmp_eq_u32_e32 vcc, 0, v1
	s_cbranch_vccnz .LBB0_87
	s_mov_b64 s[22:23], 0
	s_mov_b64 s[20:21], -1

.LBB0_167:
	global_load_dword v15, v16, s[6:7] sc1
	global_load_dword v0, v16, s[8:9] sc1
	global_load_dword v1, v16, s[10:11] sc1
	global_load_dword v2, v16, s[12:13] sc1
	global_load_dword v3, v16, s[14:15] sc1
	global_load_dword v4, v16, s[16:17] sc1
	global_load_dword v5, v16, s[18:19] sc1
	global_load_dword v6, v16, s[20:21] sc1
	global_load_dword v7, v16, s[22:23] sc1
	global_load_dword v8, v16, s[24:25] sc1
	global_load_dword v9, v16, s[26:27] sc1
	global_load_dword v10, v16, s[28:29] sc1
	global_load_dword v11, v16, s[30:31] sc1
	global_load_dword v12, v16, s[34:35] sc1
	global_load_dword v13, v16, s[36:37] sc1
	global_load_dword v14, v16, s[38:39] sc1
	s_mov_b64 s[40:41], -1
	s_mov_b64 s[42:43], -1
	s_waitcnt vmcnt(14)
	v_add_u32_e32 v17, v0, v15
	s_waitcnt vmcnt(13)
	v_add_u32_e32 v17, v17, v1
	s_waitcnt vmcnt(12)
	v_add_u32_e32 v17, v17, v2
	s_waitcnt vmcnt(11)
	v_add_u32_e32 v17, v17, v3
	s_waitcnt vmcnt(10)
	v_add_u32_e32 v17, v17, v4
	s_waitcnt vmcnt(9)
	v_add_u32_e32 v17, v17, v5
	s_waitcnt vmcnt(8)
	v_add_u32_e32 v17, v17, v6
	s_waitcnt vmcnt(7)
	v_add_u32_e32 v17, v17, v7
	s_waitcnt vmcnt(6)
	v_add_u32_e32 v17, v17, v8
	s_waitcnt vmcnt(5)
	v_add_u32_e32 v17, v17, v9
	s_waitcnt vmcnt(4)
	v_add_u32_e32 v17, v17, v10
	s_waitcnt vmcnt(3)
	v_add_u32_e32 v17, v17, v11
	s_waitcnt vmcnt(2)
	v_add_u32_e32 v17, v17, v12
	s_waitcnt vmcnt(1)
	v_add_u32_e32 v17, v17, v13
	s_waitcnt vmcnt(0)
	v_add_u32_e32 v17, v17, v14
	v_cmp_eq_u32_e32 vcc, s33, v17
	s_cbranch_vccnz .LBB0_166
	s_and_b32 s40, s46, 0xff
	s_cmp_eq_u32 s40, 0
	s_mov_b64 s[40:41], -1
	s_mov_b64 s[44:45], -1
	s_sleep 3
	s_cbranch_scc0 .LBB0_171
	global_load_dword v17, v16, s[4:5] sc1
	s_waitcnt vmcnt(0)
	v_cmp_eq_u32_e32 vcc, 0, v17
	s_cbranch_vccnz .LBB0_173
	s_mov_b64 s[44:45], 0

.LBB0_185:
	s_and_b32 s20, s24, 0xff
	s_mov_b64 s[18:19], -1
	s_cmp_lg_u32 s20, 0
	s_mov_b64 s[22:23], -1
	s_sleep 3
	s_cbranch_scc1 .LBB0_188
	global_load_dword v2, v0, s[10:11] sc1
	s_waitcnt vmcnt(0)
	v_cmp_eq_u32_e32 vcc, 0, v2
	s_cbranch_vccnz .LBB0_190
	s_mov_b64 s[22:23], 0
	s_mov_b64 s[20:21], -1

.LBB0_202:
	s_and_b32 s18, s24, 0xff
	s_cmp_lg_u32 s18, 0
	s_mov_b64 s[20:21], -1
	s_sleep 3
	s_cbranch_scc1 .LBB0_205
	global_load_dword v1, v0, s[10:11] sc1
	s_waitcnt vmcnt(0)
	v_cmp_eq_u32_e32 vcc, 0, v1
	s_cbranch_vccnz .LBB0_207
	s_mov_b64 s[20:21], 0
	s_mov_b64 s[18:19], -1

.LBB0_408:
	global_load_dword v15, v16, s[4:5] sc1
	global_load_dword v0, v16, s[6:7] sc1
	global_load_dword v1, v16, s[8:9] sc1
	global_load_dword v2, v16, s[10:11] sc1
	global_load_dword v3, v16, s[12:13] sc1
	global_load_dword v4, v16, s[14:15] sc1
	global_load_dword v5, v16, s[16:17] sc1
	global_load_dword v6, v16, s[18:19] sc1
	global_load_dword v7, v16, s[20:21] sc1
	global_load_dword v8, v16, s[22:23] sc1
	global_load_dword v9, v16, s[24:25] sc1
	global_load_dword v10, v16, s[26:27] sc1
	global_load_dword v11, v16, s[28:29] sc1
	global_load_dword v12, v16, s[30:31] sc1
	global_load_dword v13, v16, s[34:35] sc1
	global_load_dword v14, v16, s[36:37] sc1
	s_mov_b64 s[38:39], -1
	s_mov_b64 s[40:41], -1
	s_waitcnt vmcnt(14)
	v_add_u32_e32 v17, v0, v15
	s_waitcnt vmcnt(13)
	v_add_u32_e32 v17, v17, v1
	s_waitcnt vmcnt(12)
	v_add_u32_e32 v17, v17, v2
	s_waitcnt vmcnt(11)
	v_add_u32_e32 v17, v17, v3
	s_waitcnt vmcnt(10)
	v_add_u32_e32 v17, v17, v4
	s_waitcnt vmcnt(9)
	v_add_u32_e32 v17, v17, v5
	s_waitcnt vmcnt(8)
	v_add_u32_e32 v17, v17, v6
	s_waitcnt vmcnt(7)
	v_add_u32_e32 v17, v17, v7
	s_waitcnt vmcnt(6)
	v_add_u32_e32 v17, v17, v8
	s_waitcnt vmcnt(5)
	v_add_u32_e32 v17, v17, v9
	s_waitcnt vmcnt(4)
	v_add_u32_e32 v17, v17, v10
	s_waitcnt vmcnt(3)
	v_add_u32_e32 v17, v17, v11
	s_waitcnt vmcnt(2)
	v_add_u32_e32 v17, v17, v12
	s_waitcnt vmcnt(1)
	v_add_u32_e32 v17, v17, v13
	s_waitcnt vmcnt(0)
	v_add_u32_e32 v17, v17, v14
	v_cmp_eq_u32_e32 vcc, s33, v17
	s_cbranch_vccnz .LBB0_407
	s_and_b32 s38, s44, 0xff
	s_cmp_eq_u32 s38, 0
	s_mov_b64 s[38:39], -1
	s_mov_b64 s[42:43], -1
	s_sleep 3
	s_cbranch_scc0 .LBB0_412
	global_load_dword v17, v16, s[2:3] sc1
	s_waitcnt vmcnt(0)
	v_cmp_eq_u32_e32 vcc, 0, v17
	s_cbranch_vccnz .LBB0_414
	s_mov_b64 s[42:43], 0

.LBB0_426:
	s_and_b32 s18, s22, 0xff
	s_mov_b64 s[16:17], -1
	s_cmp_lg_u32 s18, 0
	s_mov_b64 s[20:21], -1
	s_sleep 3
	s_cbranch_scc1 .LBB0_429
	global_load_dword v2, v0, s[8:9] sc1
	s_waitcnt vmcnt(0)
	v_cmp_eq_u32_e32 vcc, 0, v2
	s_cbranch_vccnz .LBB0_431
	s_mov_b64 s[20:21], 0
	s_mov_b64 s[18:19], -1

.LBB0_443:
	s_and_b32 s16, s22, 0xff
	s_cmp_lg_u32 s16, 0
	s_mov_b64 s[18:19], -1
	s_sleep 3
	s_cbranch_scc1 .LBB0_446
	global_load_dword v1, v0, s[8:9] sc1
	s_waitcnt vmcnt(0)
	v_cmp_eq_u32_e32 vcc, 0, v1
	s_cbranch_vccnz .LBB0_448
	s_mov_b64 s[18:19], 0
	s_mov_b64 s[16:17], -1
